# attention: both cross-half exchanges (row max, softmax denominator) via v_permlane32_swap instead of ds_bpermute
# baseline (speedup 1.0000x reference)
.Lat3_nn3:
	v_max3_f32 v0, v32, v33, v34
	v_max3_f32 v1, v35, v36, v37
	v_max3_f32 v2, v38, v39, v40
	v_max3_f32 v3, v41, v42, v43
	v_max3_f32 v4, v44, v45, v46
	v_max3_f32 v5, v142, v143, v144
	v_max3_f32 v6, v145, v146, v147
	v_max3_f32 v7, v148, v149, v150
	v_max3_f32 v8, v151, v152, v153
	v_max3_f32 v9, v154, v155, v156
	v_max3_f32 v10, v158, v159, v160
	v_max3_f32 v11, v161, v162, v163
	v_max3_f32 v12, v164, v165, v166
	v_max3_f32 v13, v167, v168, v169
	v_max3_f32 v14, v170, v171, v172
	v_max3_f32 v15, v204, v205, v206
	v_max3_f32 v16, v207, v208, v209
	v_max3_f32 v17, v210, v211, v212
	v_max3_f32 v18, v213, v214, v215
	v_max3_f32 v19, v216, v217, v218
	v_max3_f32 v20, v220, v221, v222
	v_max3_f32 v21, v223, v224, v225
	v_max3_f32 v22, v226, v227, v228
	v_max3_f32 v23, v229, v230, v231
	v_max3_f32 v24, v232, v233, v234
	v_max3_f32 v0, v0, v1, v2
	v_max3_f32 v3, v3, v4, v47
	v_max3_f32 v5, v5, v6, v7
	v_max3_f32 v8, v8, v9, v157
	v_max3_f32 v10, v10, v11, v12
	v_max3_f32 v13, v13, v14, v173
	v_max3_f32 v15, v15, v16, v17
	v_max3_f32 v18, v18, v19, v219
	v_max3_f32 v20, v20, v21, v22
	v_max3_f32 v23, v23, v24, v235
	v_max_f32_e32 v0, v0, v3
	v_max_f32_e32 v5, v5, v8
	v_max_f32_e32 v10, v10, v13
	v_max_f32_e32 v15, v15, v18
	v_max_f32_e32 v20, v20, v23
	v_fma_f32 v5, v203, 1.0, v5
	v_fma_f32 v10, v203, 2.0, v10
	v_fma_f32 v20, v203, 4.0, v20
	v_fmamk_f32 v15, v203, 0x40400000, v15
	v_max3_f32 v0, v0, v5, v10
	v_max3_f32 v0, v0, v15, v20
	v_mov_b32_e32 v25, v0
	s_nop 1
	v_permlane32_swap_b32 v25, v0
	s_nop 0
	v_max3_f32 v174, v201, v0, v25
	v_sub_f32_e32 v90, v201, v174
	v_exp_f32_e32 v90, v90
	v_mov_b32_e32 v26, v174
	v_fma_f32 v27, -v203, 1.0, v174
	v_fma_f32 v28, -v203, 2.0, v174
	v_fma_f32 v30, -v203, 4.0, v174
	v_mul_f32_e32 v29, 0x40400000, v203
	v_sub_f32_e32 v29, v174, v29
	v_sub_f32_e32 v32, v32, v26
	v_sub_f32_e32 v33, v33, v26
	v_sub_f32_e32 v34, v34, v26
	v_sub_f32_e32 v35, v35, v26
	v_sub_f32_e32 v36, v36, v26
	v_sub_f32_e32 v37, v37, v26
	v_sub_f32_e32 v38, v38, v26
	v_sub_f32_e32 v39, v39, v26
	v_sub_f32_e32 v40, v40, v26
	v_sub_f32_e32 v41, v41, v26
	v_sub_f32_e32 v42, v42, v26
	v_sub_f32_e32 v43, v43, v26
	v_sub_f32_e32 v44, v44, v26
	v_sub_f32_e32 v45, v45, v26
	v_sub_f32_e32 v46, v46, v26
	v_sub_f32_e32 v47, v47, v26
	v_exp_f32_e32 v32, v32
	v_exp_f32_e32 v33, v33
	v_exp_f32_e32 v34, v34
	v_exp_f32_e32 v35, v35
	v_exp_f32_e32 v36, v36
	v_exp_f32_e32 v37, v37
	v_exp_f32_e32 v38, v38
	v_exp_f32_e32 v39, v39
	v_exp_f32_e32 v40, v40
	v_exp_f32_e32 v41, v41
	v_exp_f32_e32 v42, v42
	v_exp_f32_e32 v43, v43
	v_exp_f32_e32 v44, v44
	v_exp_f32_e32 v45, v45
	v_exp_f32_e32 v46, v46
	v_exp_f32_e32 v47, v47
	v_mov_b32_e32 v2, v32
	v_mov_b32_e32 v3, v33
	v_mov_b32_e32 v4, v34
	v_mov_b32_e32 v5, v35
	v_pk_add_f32 v[2:3], v[2:3], v[36:37]
	v_pk_add_f32 v[4:5], v[4:5], v[38:39]
	v_pk_add_f32 v[2:3], v[2:3], v[40:41]
	v_pk_add_f32 v[4:5], v[4:5], v[42:43]
	v_pk_add_f32 v[2:3], v[2:3], v[44:45]
	v_pk_add_f32 v[4:5], v[4:5], v[46:47]
	v_cvt_pk_bf16_f32 v32, v32, v33
	v_cvt_pk_bf16_f32 v33, v34, v35
	v_cvt_pk_bf16_f32 v34, v36, v37
	v_cvt_pk_bf16_f32 v35, v38, v39
	v_cvt_pk_bf16_f32 v36, v40, v41
	v_cvt_pk_bf16_f32 v37, v42, v43
	v_cvt_pk_bf16_f32 v38, v44, v45
	v_cvt_pk_bf16_f32 v39, v46, v47
	v_sub_f32_e32 v142, v142, v27
	v_sub_f32_e32 v143, v143, v27
	v_sub_f32_e32 v144, v144, v27
	v_sub_f32_e32 v145, v145, v27
	v_sub_f32_e32 v146, v146, v27
	v_sub_f32_e32 v147, v147, v27
	v_sub_f32_e32 v148, v148, v27
	v_sub_f32_e32 v149, v149, v27
	v_sub_f32_e32 v150, v150, v27
	v_sub_f32_e32 v151, v151, v27
	v_sub_f32_e32 v152, v152, v27
	v_sub_f32_e32 v153, v153, v27
	v_sub_f32_e32 v154, v154, v27
	v_sub_f32_e32 v155, v155, v27
	v_sub_f32_e32 v156, v156, v27
	v_sub_f32_e32 v157, v157, v27
	v_exp_f32_e32 v142, v142
	v_exp_f32_e32 v143, v143
	v_exp_f32_e32 v144, v144
	v_exp_f32_e32 v145, v145
	v_exp_f32_e32 v146, v146
	v_exp_f32_e32 v147, v147
	v_exp_f32_e32 v148, v148
	v_exp_f32_e32 v149, v149
	v_exp_f32_e32 v150, v150
	v_exp_f32_e32 v151, v151
	v_exp_f32_e32 v152, v152
	v_exp_f32_e32 v153, v153
	v_exp_f32_e32 v154, v154
	v_exp_f32_e32 v155, v155
	v_exp_f32_e32 v156, v156
	v_exp_f32_e32 v157, v157
	v_pk_add_f32 v[2:3], v[2:3], v[142:143]
	v_pk_add_f32 v[4:5], v[4:5], v[144:145]
	v_pk_add_f32 v[2:3], v[2:3], v[146:147]
	v_pk_add_f32 v[4:5], v[4:5], v[148:149]
	v_pk_add_f32 v[2:3], v[2:3], v[150:151]
	v_pk_add_f32 v[4:5], v[4:5], v[152:153]
	v_pk_add_f32 v[2:3], v[2:3], v[154:155]
	v_pk_add_f32 v[4:5], v[4:5], v[156:157]
	v_cvt_pk_bf16_f32 v142, v142, v143
	v_cvt_pk_bf16_f32 v143, v144, v145
	v_cvt_pk_bf16_f32 v144, v146, v147
	v_cvt_pk_bf16_f32 v145, v148, v149
	v_cvt_pk_bf16_f32 v146, v150, v151
	v_cvt_pk_bf16_f32 v147, v152, v153
	v_cvt_pk_bf16_f32 v148, v154, v155
	v_cvt_pk_bf16_f32 v149, v156, v157
	v_sub_f32_e32 v158, v158, v28
	v_sub_f32_e32 v159, v159, v28
	v_sub_f32_e32 v160, v160, v28
	v_sub_f32_e32 v161, v161, v28
	v_sub_f32_e32 v162, v162, v28
	v_sub_f32_e32 v163, v163, v28
	v_sub_f32_e32 v164, v164, v28
	v_sub_f32_e32 v165, v165, v28
	v_sub_f32_e32 v166, v166, v28
	v_sub_f32_e32 v167, v167, v28
	v_sub_f32_e32 v168, v168, v28
	v_sub_f32_e32 v169, v169, v28
	v_sub_f32_e32 v170, v170, v28
	v_sub_f32_e32 v171, v171, v28
	v_sub_f32_e32 v172, v172, v28
	v_sub_f32_e32 v173, v173, v28
	v_exp_f32_e32 v158, v158
	v_exp_f32_e32 v159, v159
	v_exp_f32_e32 v160, v160
	v_exp_f32_e32 v161, v161
	v_exp_f32_e32 v162, v162
	v_exp_f32_e32 v163, v163
	v_exp_f32_e32 v164, v164
	v_exp_f32_e32 v165, v165
	v_exp_f32_e32 v166, v166
	v_exp_f32_e32 v167, v167
	v_exp_f32_e32 v168, v168
	v_exp_f32_e32 v169, v169
	v_exp_f32_e32 v170, v170
	v_exp_f32_e32 v171, v171
	v_exp_f32_e32 v172, v172
	v_exp_f32_e32 v173, v173
	v_pk_add_f32 v[2:3], v[2:3], v[158:159]
	v_pk_add_f32 v[4:5], v[4:5], v[160:161]
	v_pk_add_f32 v[2:3], v[2:3], v[162:163]
	v_pk_add_f32 v[4:5], v[4:5], v[164:165]
	v_pk_add_f32 v[2:3], v[2:3], v[166:167]
	v_pk_add_f32 v[4:5], v[4:5], v[168:169]
	v_pk_add_f32 v[2:3], v[2:3], v[170:171]
	v_pk_add_f32 v[4:5], v[4:5], v[172:173]
	v_cvt_pk_bf16_f32 v158, v158, v159
	v_cvt_pk_bf16_f32 v159, v160, v161
	v_cvt_pk_bf16_f32 v160, v162, v163
	v_cvt_pk_bf16_f32 v161, v164, v165
	v_cvt_pk_bf16_f32 v162, v166, v167
	v_cvt_pk_bf16_f32 v163, v168, v169
	v_cvt_pk_bf16_f32 v164, v170, v171
	v_cvt_pk_bf16_f32 v165, v172, v173
	v_sub_f32_e32 v204, v204, v29
	v_sub_f32_e32 v205, v205, v29
	v_sub_f32_e32 v206, v206, v29
	v_sub_f32_e32 v207, v207, v29
	v_sub_f32_e32 v208, v208, v29
	v_sub_f32_e32 v209, v209, v29
	v_sub_f32_e32 v210, v210, v29
	v_sub_f32_e32 v211, v211, v29
	v_sub_f32_e32 v212, v212, v29
	v_sub_f32_e32 v213, v213, v29
	v_sub_f32_e32 v214, v214, v29
	v_sub_f32_e32 v215, v215, v29
	v_sub_f32_e32 v216, v216, v29
	v_sub_f32_e32 v217, v217, v29
	v_sub_f32_e32 v218, v218, v29
	v_sub_f32_e32 v219, v219, v29
	v_exp_f32_e32 v204, v204
	v_exp_f32_e32 v205, v205
	v_exp_f32_e32 v206, v206
	v_exp_f32_e32 v207, v207
	v_exp_f32_e32 v208, v208
	v_exp_f32_e32 v209, v209
	v_exp_f32_e32 v210, v210
	v_exp_f32_e32 v211, v211
	v_exp_f32_e32 v212, v212
	v_exp_f32_e32 v213, v213
	v_exp_f32_e32 v214, v214
	v_exp_f32_e32 v215, v215
	v_exp_f32_e32 v216, v216
	v_exp_f32_e32 v217, v217
	v_exp_f32_e32 v218, v218
	v_exp_f32_e32 v219, v219
	v_pk_add_f32 v[2:3], v[2:3], v[204:205]
	v_pk_add_f32 v[4:5], v[4:5], v[206:207]
	v_pk_add_f32 v[2:3], v[2:3], v[208:209]
	v_pk_add_f32 v[4:5], v[4:5], v[210:211]
	v_pk_add_f32 v[2:3], v[2:3], v[212:213]
	v_pk_add_f32 v[4:5], v[4:5], v[214:215]
	v_pk_add_f32 v[2:3], v[2:3], v[216:217]
	v_pk_add_f32 v[4:5], v[4:5], v[218:219]
	v_cvt_pk_bf16_f32 v204, v204, v205
	v_cvt_pk_bf16_f32 v205, v206, v207
	v_cvt_pk_bf16_f32 v206, v208, v209
	v_cvt_pk_bf16_f32 v207, v210, v211
	v_cvt_pk_bf16_f32 v208, v212, v213
	v_cvt_pk_bf16_f32 v209, v214, v215
	v_cvt_pk_bf16_f32 v210, v216, v217
	v_cvt_pk_bf16_f32 v211, v218, v219
	v_sub_f32_e32 v220, v220, v30
	v_sub_f32_e32 v221, v221, v30
	v_sub_f32_e32 v222, v222, v30
	v_sub_f32_e32 v223, v223, v30
	v_sub_f32_e32 v224, v224, v30
	v_sub_f32_e32 v225, v225, v30
	v_sub_f32_e32 v226, v226, v30
	v_sub_f32_e32 v227, v227, v30
	v_sub_f32_e32 v228, v228, v30
	v_sub_f32_e32 v229, v229, v30
	v_sub_f32_e32 v230, v230, v30
	v_sub_f32_e32 v231, v231, v30
	v_sub_f32_e32 v232, v232, v30
	v_sub_f32_e32 v233, v233, v30
	v_sub_f32_e32 v234, v234, v30
	v_sub_f32_e32 v235, v235, v30
	v_exp_f32_e32 v220, v220
	v_exp_f32_e32 v221, v221
	v_exp_f32_e32 v222, v222
	v_exp_f32_e32 v223, v223
	v_exp_f32_e32 v224, v224
	v_exp_f32_e32 v225, v225
	v_exp_f32_e32 v226, v226
	v_exp_f32_e32 v227, v227
	v_exp_f32_e32 v228, v228
	v_exp_f32_e32 v229, v229
	v_exp_f32_e32 v230, v230
	v_exp_f32_e32 v231, v231
	v_exp_f32_e32 v232, v232
	v_exp_f32_e32 v233, v233
	v_exp_f32_e32 v234, v234
	v_exp_f32_e32 v235, v235
	v_pk_add_f32 v[2:3], v[2:3], v[220:221]
	v_pk_add_f32 v[4:5], v[4:5], v[222:223]
	v_pk_add_f32 v[2:3], v[2:3], v[224:225]
	v_pk_add_f32 v[4:5], v[4:5], v[226:227]
	v_pk_add_f32 v[2:3], v[2:3], v[228:229]
	v_pk_add_f32 v[4:5], v[4:5], v[230:231]
	v_pk_add_f32 v[2:3], v[2:3], v[232:233]
	v_pk_add_f32 v[4:5], v[4:5], v[234:235]
	v_cvt_pk_bf16_f32 v220, v220, v221
	v_cvt_pk_bf16_f32 v221, v222, v223
	v_cvt_pk_bf16_f32 v222, v224, v225
	v_cvt_pk_bf16_f32 v223, v226, v227
	v_cvt_pk_bf16_f32 v224, v228, v229
	v_cvt_pk_bf16_f32 v225, v230, v231
	v_cvt_pk_bf16_f32 v226, v232, v233
	v_cvt_pk_bf16_f32 v227, v234, v235
	s_nop 1
	ds_read_b64_tr_b16 v[40:41], v252
	ds_read_b64_tr_b16 v[42:43], v252 offset:576
	ds_read_b64_tr_b16 v[44:45], v252 offset:64
	ds_read_b64_tr_b16 v[46:47], v252 offset:640
	ds_read_b64_tr_b16 v[150:151], v252 offset:2304
	ds_read_b64_tr_b16 v[152:153], v252 offset:2880
	ds_read_b64_tr_b16 v[154:155], v252 offset:2368
	ds_read_b64_tr_b16 v[156:157], v252 offset:2944
	v_pk_add_f32 v[2:3], v[2:3], v[4:5]
	s_nop 0
	v_add_f32_e32 v175, v2, v3
	v_fmac_f32_e32 v175, v89, v90
	s_waitcnt lgkmcnt(6)
	v_mfma_f32_32x32x16_bf16 v[0:15], v[40:43], v[32:35], 0
	s_waitcnt lgkmcnt(4)
	v_mfma_f32_32x32x16_bf16 v[16:31], v[44:47], v[32:35], 0
	ds_read_b64_tr_b16 v[40:41], v252 offset:4608
	ds_read_b64_tr_b16 v[42:43], v252 offset:5184
	ds_read_b64_tr_b16 v[44:45], v252 offset:4672
	ds_read_b64_tr_b16 v[46:47], v252 offset:5248
	s_waitcnt lgkmcnt(6)
	v_mfma_f32_32x32x16_bf16 v[0:15], v[150:153], v[36:39], v[0:15]
	s_waitcnt lgkmcnt(4)
	v_mfma_f32_32x32x16_bf16 v[16:31], v[154:157], v[36:39], v[16:31]
	ds_read_b64_tr_b16 v[150:151], v252 offset:6912
	ds_read_b64_tr_b16 v[152:153], v252 offset:7488
	ds_read_b64_tr_b16 v[154:155], v252 offset:6976
	ds_read_b64_tr_b16 v[156:157], v252 offset:7552
	s_waitcnt lgkmcnt(6)
	v_mfma_f32_32x32x16_bf16 v[0:15], v[40:43], v[142:145], v[0:15]
	s_waitcnt lgkmcnt(4)
	v_mfma_f32_32x32x16_bf16 v[16:31], v[44:47], v[142:145], v[16:31]
	ds_read_b64_tr_b16 v[40:41], v252 offset:9216
	ds_read_b64_tr_b16 v[42:43], v252 offset:9792
	ds_read_b64_tr_b16 v[44:45], v252 offset:9280
	ds_read_b64_tr_b16 v[46:47], v252 offset:9856
	s_waitcnt lgkmcnt(6)
	v_mfma_f32_32x32x16_bf16 v[0:15], v[150:153], v[146:149], v[0:15]
	s_waitcnt lgkmcnt(4)
	v_mfma_f32_32x32x16_bf16 v[16:31], v[154:157], v[146:149], v[16:31]
	ds_read_b64_tr_b16 v[150:151], v252 offset:11520
	ds_read_b64_tr_b16 v[152:153], v252 offset:12096
	ds_read_b64_tr_b16 v[154:155], v252 offset:11584
	ds_read_b64_tr_b16 v[156:157], v252 offset:12160
	s_waitcnt lgkmcnt(6)
	v_mfma_f32_32x32x16_bf16 v[0:15], v[40:43], v[158:161], v[0:15]
	s_waitcnt lgkmcnt(4)
	v_mfma_f32_32x32x16_bf16 v[16:31], v[44:47], v[158:161], v[16:31]
	ds_read_b64_tr_b16 v[40:41], v252 offset:13824
	ds_read_b64_tr_b16 v[42:43], v252 offset:14400
	ds_read_b64_tr_b16 v[44:45], v252 offset:13888
	ds_read_b64_tr_b16 v[46:47], v252 offset:14464
	s_waitcnt lgkmcnt(6)
	v_mfma_f32_32x32x16_bf16 v[0:15], v[150:153], v[162:165], v[0:15]
	s_waitcnt lgkmcnt(4)
	v_mfma_f32_32x32x16_bf16 v[16:31], v[154:157], v[162:165], v[16:31]
	ds_read_b64_tr_b16 v[150:151], v252 offset:16128
	ds_read_b64_tr_b16 v[152:153], v252 offset:16704
	ds_read_b64_tr_b16 v[154:155], v252 offset:16192
	ds_read_b64_tr_b16 v[156:157], v252 offset:16768
	s_waitcnt lgkmcnt(6)
	v_mfma_f32_32x32x16_bf16 v[0:15], v[40:43], v[204:207], v[0:15]
	s_waitcnt lgkmcnt(4)
	v_mfma_f32_32x32x16_bf16 v[16:31], v[44:47], v[204:207], v[16:31]
	ds_read_b64_tr_b16 v[40:41], v252 offset:18432
	ds_read_b64_tr_b16 v[42:43], v252 offset:19008
	ds_read_b64_tr_b16 v[44:45], v252 offset:18496
	ds_read_b64_tr_b16 v[46:47], v252 offset:19072
	s_waitcnt lgkmcnt(6)
	v_mfma_f32_32x32x16_bf16 v[0:15], v[150:153], v[208:211], v[0:15]
	s_waitcnt lgkmcnt(4)
	v_mfma_f32_32x32x16_bf16 v[16:31], v[154:157], v[208:211], v[16:31]
	ds_read_b64_tr_b16 v[150:151], v252 offset:20736
	ds_read_b64_tr_b16 v[152:153], v252 offset:21312
	ds_read_b64_tr_b16 v[154:155], v252 offset:20800
	ds_read_b64_tr_b16 v[156:157], v252 offset:21376
	s_waitcnt lgkmcnt(6)
	v_mfma_f32_32x32x16_bf16 v[0:15], v[40:43], v[220:223], v[0:15]
	s_waitcnt lgkmcnt(4)
	v_mfma_f32_32x32x16_bf16 v[16:31], v[44:47], v[220:223], v[16:31]
	s_waitcnt lgkmcnt(2)
	v_mfma_f32_32x32x16_bf16 v[0:15], v[150:153], v[224:227], v[0:15]
	s_waitcnt lgkmcnt(0)
	v_mfma_f32_32x32x16_bf16 v[16:31], v[154:157], v[224:227], v[16:31]
	v_mov_b32_e32 v37, v174
	v_mov_b32_e32 v38, v175
.LBB0_427:
	v_mov_b32_e32 v32, v38
	s_nop 1
	v_permlane32_swap_b32 v32, v38
	s_add_u32 s8, s58, s78
	s_addc_u32 s9, s59, s79
	s_ashr_i32 s7, s6, 31
	s_lshl_b64 s[6:7], s[6:7], 14
	s_nop 0
	v_add_f32_e32 v36, v38, v32
	v_div_scale_f32 v32, s[10:11], v36, v36, 1.0
	v_rcp_f32_e32 v33, v32
	v_div_scale_f32 v34, vcc, 1.0, v36, 1.0
	s_add_u32 s6, s6, s67
	v_fma_f32 v35, -v32, v33, 1.0
	v_fmac_f32_e32 v33, v35, v33
	v_mul_f32_e32 v35, v34, v33
	v_fma_f32 v38, -v32, v35, v34
	v_fmac_f32_e32 v35, v38, v33
	v_fma_f32 v32, -v32, v35, v34
	v_div_fmas_f32 v32, v32, v33, v35
	s_addc_u32 s7, s7, 0
	v_div_fixup_f32 v42, v32, v36, 1.0
	v_add_u32_e32 v34, s13, v139
	v_mov_b64_e32 v[32:33], s[6:7]
	v_ashrrev_i32_e32 v38, 31, v34
	v_mad_u64_u32 v[34:35], s[6:7], v34, s1, v[32:33]
	v_mov_b32_e32 v32, v35
	v_mad_u64_u32 v[32:33], s[6:7], v38, s1, v[32:33]
	v_mad_u64_u32 v[38:39], s[6:7], v34, s68, 0
	v_mov_b32_e32 v40, v39
	v_mad_u64_u32 v[40:41], s[6:7], v32, s68, v[40:41]
	v_mov_b32_e32 v39, v40
	v_lshl_add_u64 v[38:39], v[38:39], 1, s[8:9]
	s_ashr_i32 s13, s12, 31
	v_lshl_add_u64 v[38:39], s[12:13], 1, v[38:39]
	v_mov_b32_e32 v141, v88
	v_lshl_add_u64 v[38:39], v[38:39], 0, v[140:141]
	s_cmp_gt_i32 s0, -1
	s_cselect_b64 s[6:7], -1, 0
	s_and_b64 s[8:9], s[6:7], s[4:5]
	v_mbcnt_lo_u32_b32 v40, -1, 0
	v_mbcnt_hi_u32_b32 v40, -1, v40
	v_and_b32_e32 v40, 32, v40
	v_lshrrev_b32_e32 v40, 2, v40
	v_mov_b32_e32 v41, 0
	v_lshl_add_u64 v[38:39], v[38:39], 0, v[40:41]
	v_mul_f32_e32 v0, v0, v42
	v_mul_f32_e32 v1, v1, v42
	v_mul_f32_e32 v2, v2, v42
	v_mul_f32_e32 v3, v3, v42
	v_mul_f32_e32 v4, v4, v42
	v_mul_f32_e32 v5, v5, v42
	v_mul_f32_e32 v6, v6, v42
	v_mul_f32_e32 v7, v7, v42
	v_cvt_pk_bf16_f32 v0, v0, v1
	v_cvt_pk_bf16_f32 v1, v2, v3
	v_cvt_pk_bf16_f32 v2, v4, v5
	v_cvt_pk_bf16_f32 v3, v6, v7
	s_nop 1
	v_permlane32_swap_b32 v0, v2
	v_permlane32_swap_b32 v1, v3
	global_store_dwordx4 v[38:39], v[0:3], off
	v_mul_f32_e32 v8, v8, v42
	v_mul_f32_e32 v9, v9, v42
	v_mul_f32_e32 v10, v10, v42
	v_mul_f32_e32 v11, v11, v42
	v_mul_f32_e32 v12, v12, v42
	v_mul_f32_e32 v13, v13, v42
	v_mul_f32_e32 v14, v14, v42
	v_mul_f32_e32 v15, v15, v42
	v_cvt_pk_bf16_f32 v8, v8, v9
	v_cvt_pk_bf16_f32 v9, v10, v11
	v_cvt_pk_bf16_f32 v10, v12, v13
	v_cvt_pk_bf16_f32 v11, v14, v15
	s_nop 1
	v_permlane32_swap_b32 v8, v10
	v_permlane32_swap_b32 v9, v11
	global_store_dwordx4 v[38:39], v[8:11], off offset:32
	v_mul_f32_e32 v16, v16, v42
	v_mul_f32_e32 v17, v17, v42
	v_mul_f32_e32 v18, v18, v42
	v_mul_f32_e32 v19, v19, v42
	v_mul_f32_e32 v20, v20, v42
	v_mul_f32_e32 v21, v21, v42
	v_mul_f32_e32 v22, v22, v42
	v_mul_f32_e32 v23, v23, v42
	v_cvt_pk_bf16_f32 v16, v16, v17
	v_cvt_pk_bf16_f32 v17, v18, v19
	v_cvt_pk_bf16_f32 v18, v20, v21
	v_cvt_pk_bf16_f32 v19, v22, v23
	s_nop 1
	v_permlane32_swap_b32 v16, v18
	v_permlane32_swap_b32 v17, v19
	global_store_dwordx4 v[38:39], v[16:19], off offset:64
	v_mul_f32_e32 v24, v24, v42
	v_mul_f32_e32 v25, v25, v42
	v_mul_f32_e32 v26, v26, v42
	v_mul_f32_e32 v27, v27, v42
	v_mul_f32_e32 v28, v28, v42
	v_mul_f32_e32 v29, v29, v42
	v_mul_f32_e32 v30, v30, v42
	v_mul_f32_e32 v31, v31, v42
	v_cvt_pk_bf16_f32 v24, v24, v25
	v_cvt_pk_bf16_f32 v25, v26, v27
	v_cvt_pk_bf16_f32 v26, v28, v29
	v_cvt_pk_bf16_f32 v27, v30, v31
	s_nop 1
	v_permlane32_swap_b32 v24, v26
	v_permlane32_swap_b32 v25, v27
	global_store_dwordx4 v[38:39], v[24:27], off offset:96
	s_and_saveexec_b64 s[6:7], s[8:9]
	s_cbranch_execz .LBB0_385
	v_log_f32_e32 v2, v36
	v_readlane_b32 s8, v255, 22
	v_readlane_b32 s9, v255, 23
	s_mov_b32 s1, s15
	v_add_f32_e32 v4, v37, v2
	v_mad_u64_u32 v[0:1], s[8:9], v34, 48, s[8:9]
	v_mov_b32_e32 v2, v1
	v_mad_u64_u32 v[2:3], s[8:9], v32, 48, v[2:3]
	v_mov_b32_e32 v1, v2
	v_lshl_add_u64 v[0:1], s[0:1], 2, v[0:1]
	global_store_dword v[0:1], v4, off
	s_branch .LBB0_385

.LBB0_1287:
	v_mov_b32_e32 v32, v38
	s_nop 1
	v_permlane32_swap_b32 v32, v38
	s_add_u32 s10, s58, s74
	s_addc_u32 s11, s59, s75
	s_ashr_i32 s5, s4, 31
	s_lshl_b64 s[4:5], s[4:5], 14
	s_nop 0
	v_add_f32_e32 v36, v38, v32
	v_div_scale_f32 v32, s[12:13], v36, v36, 1.0
	v_rcp_f32_e32 v33, v32
	v_div_scale_f32 v34, vcc, 1.0, v36, 1.0
	s_add_u32 s4, s4, s65
	v_fma_f32 v35, -v32, v33, 1.0
	v_fmac_f32_e32 v33, v35, v33
	v_mul_f32_e32 v35, v34, v33
	v_fma_f32 v38, -v32, v35, v34
	v_fmac_f32_e32 v35, v38, v33
	v_fma_f32 v32, -v32, v35, v34
	v_div_fmas_f32 v32, v32, v33, v35
	s_addc_u32 s5, s5, 0
	v_div_fixup_f32 v42, v32, v36, 1.0
	v_add_u32_e32 v34, s7, v139
	v_mov_b64_e32 v[32:33], s[4:5]
	v_ashrrev_i32_e32 v38, 31, v34
	v_mad_u64_u32 v[34:35], s[4:5], v34, s1, v[32:33]
	v_mov_b32_e32 v32, v35
	v_mad_u64_u32 v[32:33], s[4:5], v38, s1, v[32:33]
	v_mad_u64_u32 v[38:39], s[4:5], v34, s66, 0
	v_mov_b32_e32 v40, v39
	v_mad_u64_u32 v[40:41], s[4:5], v32, s66, v[40:41]
	v_mov_b32_e32 v39, v40
	v_lshl_add_u64 v[38:39], v[38:39], 1, s[10:11]
	s_ashr_i32 s7, s6, 31
	v_lshl_add_u64 v[38:39], s[6:7], 1, v[38:39]
	v_mov_b32_e32 v141, v88
	v_lshl_add_u64 v[38:39], v[38:39], 0, v[140:141]
	s_cmp_gt_i32 s0, -1
	s_cselect_b64 s[4:5], -1, 0
	s_and_b64 s[6:7], s[4:5], s[8:9]
	v_mbcnt_lo_u32_b32 v40, -1, 0
	v_mbcnt_hi_u32_b32 v40, -1, v40
	v_and_b32_e32 v40, 32, v40
	v_lshrrev_b32_e32 v40, 2, v40
	v_mov_b32_e32 v41, 0
	v_lshl_add_u64 v[38:39], v[38:39], 0, v[40:41]
	v_mul_f32_e32 v0, v0, v42
	v_mul_f32_e32 v1, v1, v42
	v_mul_f32_e32 v2, v2, v42
	v_mul_f32_e32 v3, v3, v42
	v_mul_f32_e32 v4, v4, v42
	v_mul_f32_e32 v5, v5, v42
	v_mul_f32_e32 v6, v6, v42
	v_mul_f32_e32 v7, v7, v42
	v_cvt_pk_bf16_f32 v0, v0, v1
	v_cvt_pk_bf16_f32 v1, v2, v3
	v_cvt_pk_bf16_f32 v2, v4, v5
	v_cvt_pk_bf16_f32 v3, v6, v7
	s_nop 1
	v_permlane32_swap_b32 v0, v2
	v_permlane32_swap_b32 v1, v3
	global_store_dwordx4 v[38:39], v[0:3], off
	v_mul_f32_e32 v8, v8, v42
	v_mul_f32_e32 v9, v9, v42
	v_mul_f32_e32 v10, v10, v42
	v_mul_f32_e32 v11, v11, v42
	v_mul_f32_e32 v12, v12, v42
	v_mul_f32_e32 v13, v13, v42
	v_mul_f32_e32 v14, v14, v42
	v_mul_f32_e32 v15, v15, v42
	v_cvt_pk_bf16_f32 v8, v8, v9
	v_cvt_pk_bf16_f32 v9, v10, v11
	v_cvt_pk_bf16_f32 v10, v12, v13
	v_cvt_pk_bf16_f32 v11, v14, v15
	s_nop 1
	v_permlane32_swap_b32 v8, v10
	v_permlane32_swap_b32 v9, v11
	global_store_dwordx4 v[38:39], v[8:11], off offset:32
	v_mul_f32_e32 v16, v16, v42
	v_mul_f32_e32 v17, v17, v42
	v_mul_f32_e32 v18, v18, v42
	v_mul_f32_e32 v19, v19, v42
	v_mul_f32_e32 v20, v20, v42
	v_mul_f32_e32 v21, v21, v42
	v_mul_f32_e32 v22, v22, v42
	v_mul_f32_e32 v23, v23, v42
	v_cvt_pk_bf16_f32 v16, v16, v17
	v_cvt_pk_bf16_f32 v17, v18, v19
	v_cvt_pk_bf16_f32 v18, v20, v21
	v_cvt_pk_bf16_f32 v19, v22, v23
	s_nop 1
	v_permlane32_swap_b32 v16, v18
	v_permlane32_swap_b32 v17, v19
	global_store_dwordx4 v[38:39], v[16:19], off offset:64
	v_mul_f32_e32 v24, v24, v42
	v_mul_f32_e32 v25, v25, v42
	v_mul_f32_e32 v26, v26, v42
	v_mul_f32_e32 v27, v27, v42
	v_mul_f32_e32 v28, v28, v42
	v_mul_f32_e32 v29, v29, v42
	v_mul_f32_e32 v30, v30, v42
	v_mul_f32_e32 v31, v31, v42
	v_cvt_pk_bf16_f32 v24, v24, v25
	v_cvt_pk_bf16_f32 v25, v26, v27
	v_cvt_pk_bf16_f32 v26, v28, v29
	v_cvt_pk_bf16_f32 v27, v30, v31
	s_nop 1
	v_permlane32_swap_b32 v24, v26
	v_permlane32_swap_b32 v25, v27
	global_store_dwordx4 v[38:39], v[24:27], off offset:96
	s_and_saveexec_b64 s[4:5], s[6:7]
	s_cbranch_execz .LBB0_1245
	v_log_f32_e32 v2, v36
	v_readlane_b32 s6, v255, 22
	v_readlane_b32 s7, v255, 23
	s_mov_b32 s1, s15
	v_add_f32_e32 v4, v37, v2
	v_mad_u64_u32 v[0:1], s[6:7], v34, 48, s[6:7]
	v_mov_b32_e32 v2, v1
	v_mad_u64_u32 v[2:3], s[6:7], v32, 48, v[2:3]
	v_mov_b32_e32 v1, v2
	v_lshl_add_u64 v[0:1], s[0:1], 2, v[0:1]
	global_store_dword v[0:1], v4, off
	s_branch .LBB0_1245

.LBB0_2147:
	v_mov_b32_e32 v32, v38
	s_nop 1
	v_permlane32_swap_b32 v32, v38
	s_add_u32 s12, s58, s46
	s_addc_u32 s13, s59, s47
	s_ashr_i32 s5, s4, 31
	s_lshl_b64 s[4:5], s[4:5], 14
	s_nop 0
	v_add_f32_e32 v36, v38, v32
	v_div_scale_f32 v32, s[14:15], v36, v36, 1.0
	v_rcp_f32_e32 v33, v32
	v_div_scale_f32 v34, vcc, 1.0, v36, 1.0
	s_add_u32 s4, s4, s65
	v_fma_f32 v35, -v32, v33, 1.0
	v_fmac_f32_e32 v33, v35, v33
	v_mul_f32_e32 v35, v34, v33
	v_fma_f32 v38, -v32, v35, v34
	v_fmac_f32_e32 v35, v38, v33
	v_fma_f32 v32, -v32, v35, v34
	v_div_fmas_f32 v32, v32, v33, v35
	s_addc_u32 s5, s5, 0
	v_div_fixup_f32 v42, v32, v36, 1.0
	v_add_u32_e32 v34, s7, v139
	v_mov_b64_e32 v[32:33], s[4:5]
	v_ashrrev_i32_e32 v38, 31, v34
	v_mad_u64_u32 v[34:35], s[4:5], v34, s1, v[32:33]
	v_mov_b32_e32 v32, v35
	v_mad_u64_u32 v[32:33], s[4:5], v38, s1, v[32:33]
	v_mad_u64_u32 v[38:39], s[4:5], v34, s66, 0
	v_mov_b32_e32 v40, v39
	v_mad_u64_u32 v[40:41], s[4:5], v32, s66, v[40:41]
	v_mov_b32_e32 v39, v40
	v_lshl_add_u64 v[38:39], v[38:39], 1, s[12:13]
	s_ashr_i32 s7, s6, 31
	v_lshl_add_u64 v[38:39], s[6:7], 1, v[38:39]
	v_mov_b32_e32 v141, v88
	v_lshl_add_u64 v[38:39], v[38:39], 0, v[140:141]
	s_cmp_gt_i32 s0, -1
	s_cselect_b64 s[4:5], -1, 0
	s_and_b64 s[6:7], s[4:5], s[10:11]
	v_mbcnt_lo_u32_b32 v40, -1, 0
	v_mbcnt_hi_u32_b32 v40, -1, v40
	v_and_b32_e32 v40, 32, v40
	v_lshrrev_b32_e32 v40, 2, v40
	v_mov_b32_e32 v41, 0
	v_lshl_add_u64 v[38:39], v[38:39], 0, v[40:41]
	v_mul_f32_e32 v0, v0, v42
	v_mul_f32_e32 v1, v1, v42
	v_mul_f32_e32 v2, v2, v42
	v_mul_f32_e32 v3, v3, v42
	v_mul_f32_e32 v4, v4, v42
	v_mul_f32_e32 v5, v5, v42
	v_mul_f32_e32 v6, v6, v42
	v_mul_f32_e32 v7, v7, v42
	v_cvt_pk_bf16_f32 v0, v0, v1
	v_cvt_pk_bf16_f32 v1, v2, v3
	v_cvt_pk_bf16_f32 v2, v4, v5
	v_cvt_pk_bf16_f32 v3, v6, v7
	s_nop 1
	v_permlane32_swap_b32 v0, v2
	v_permlane32_swap_b32 v1, v3
	global_store_dwordx4 v[38:39], v[0:3], off
	v_mul_f32_e32 v8, v8, v42
	v_mul_f32_e32 v9, v9, v42
	v_mul_f32_e32 v10, v10, v42
	v_mul_f32_e32 v11, v11, v42
	v_mul_f32_e32 v12, v12, v42
	v_mul_f32_e32 v13, v13, v42
	v_mul_f32_e32 v14, v14, v42
	v_mul_f32_e32 v15, v15, v42
	v_cvt_pk_bf16_f32 v8, v8, v9
	v_cvt_pk_bf16_f32 v9, v10, v11
	v_cvt_pk_bf16_f32 v10, v12, v13
	v_cvt_pk_bf16_f32 v11, v14, v15
	s_nop 1
	v_permlane32_swap_b32 v8, v10
	v_permlane32_swap_b32 v9, v11
	global_store_dwordx4 v[38:39], v[8:11], off offset:32
	v_mul_f32_e32 v16, v16, v42
	v_mul_f32_e32 v17, v17, v42
	v_mul_f32_e32 v18, v18, v42
	v_mul_f32_e32 v19, v19, v42
	v_mul_f32_e32 v20, v20, v42
	v_mul_f32_e32 v21, v21, v42
	v_mul_f32_e32 v22, v22, v42
	v_mul_f32_e32 v23, v23, v42
	v_cvt_pk_bf16_f32 v16, v16, v17
	v_cvt_pk_bf16_f32 v17, v18, v19
	v_cvt_pk_bf16_f32 v18, v20, v21
	v_cvt_pk_bf16_f32 v19, v22, v23
	s_nop 1
	v_permlane32_swap_b32 v16, v18
	v_permlane32_swap_b32 v17, v19
	global_store_dwordx4 v[38:39], v[16:19], off offset:64
	v_mul_f32_e32 v24, v24, v42
	v_mul_f32_e32 v25, v25, v42
	v_mul_f32_e32 v26, v26, v42
	v_mul_f32_e32 v27, v27, v42
	v_mul_f32_e32 v28, v28, v42
	v_mul_f32_e32 v29, v29, v42
	v_mul_f32_e32 v30, v30, v42
	v_mul_f32_e32 v31, v31, v42
	v_cvt_pk_bf16_f32 v24, v24, v25
	v_cvt_pk_bf16_f32 v25, v26, v27
	v_cvt_pk_bf16_f32 v26, v28, v29
	v_cvt_pk_bf16_f32 v27, v30, v31
	s_nop 1
	v_permlane32_swap_b32 v24, v26
	v_permlane32_swap_b32 v25, v27
	global_store_dwordx4 v[38:39], v[24:27], off offset:96
	s_and_saveexec_b64 s[4:5], s[6:7]
	s_cbranch_execz .LBB0_2105
	v_log_f32_e32 v2, v36
	v_readlane_b32 s6, v255, 22
	v_readlane_b32 s7, v255, 23
	s_mov_b32 s1, s9
	v_add_f32_e32 v4, v37, v2
	v_mad_u64_u32 v[0:1], s[6:7], v34, 48, s[6:7]
	v_mov_b32_e32 v2, v1
	v_mad_u64_u32 v[2:3], s[6:7], v32, 48, v[2:3]
	v_mov_b32_e32 v1, v2
	v_lshl_add_u64 v[0:1], s[0:1], 2, v[0:1]
	global_store_dword v[0:1], v4, off
	s_branch .LBB0_2105

.LBB0_3011:
	v_mov_b32_e32 v32, v38
	s_nop 1
	v_permlane32_swap_b32 v32, v38
	s_add_u32 s10, s58, s46
	s_addc_u32 s11, s59, s47
	s_ashr_i32 s5, s4, 31
	s_lshl_b64 s[4:5], s[4:5], 14
	s_nop 0
	v_add_f32_e32 v36, v38, v32
	v_div_scale_f32 v32, s[12:13], v36, v36, 1.0
	v_rcp_f32_e32 v33, v32
	v_div_scale_f32 v34, vcc, 1.0, v36, 1.0
	s_add_u32 s4, s4, s53
	v_fma_f32 v35, -v32, v33, 1.0
	v_fmac_f32_e32 v33, v35, v33
	v_mul_f32_e32 v35, v34, v33
	v_fma_f32 v38, -v32, v35, v34
	v_fmac_f32_e32 v35, v38, v33
	v_fma_f32 v32, -v32, v35, v34
	v_div_fmas_f32 v32, v32, v33, v35
	s_addc_u32 s5, s5, 0
	v_div_fixup_f32 v42, v32, v36, 1.0
	v_add_u32_e32 v34, s9, v139
	v_mov_b64_e32 v[32:33], s[4:5]
	v_ashrrev_i32_e32 v38, 31, v34
	v_mad_u64_u32 v[34:35], s[4:5], v34, s1, v[32:33]
	v_mov_b32_e32 v32, v35
	v_mad_u64_u32 v[32:33], s[4:5], v38, s1, v[32:33]
	v_mad_u64_u32 v[38:39], s[4:5], v34, s54, 0
	v_mov_b32_e32 v40, v39
	v_mad_u64_u32 v[40:41], s[4:5], v32, s54, v[40:41]
	v_mov_b32_e32 v39, v40
	v_lshl_add_u64 v[38:39], v[38:39], 1, s[10:11]
	s_ashr_i32 s9, s8, 31
	v_lshl_add_u64 v[38:39], s[8:9], 1, v[38:39]
	v_mov_b32_e32 v141, v88
	v_lshl_add_u64 v[38:39], v[38:39], 0, v[140:141]
	s_cmp_gt_i32 s0, -1
	s_cselect_b64 s[4:5], -1, 0
	s_and_b64 s[8:9], s[4:5], s[6:7]
	v_mbcnt_lo_u32_b32 v40, -1, 0
	v_mbcnt_hi_u32_b32 v40, -1, v40
	v_and_b32_e32 v40, 32, v40
	v_lshrrev_b32_e32 v40, 2, v40
	v_mov_b32_e32 v41, 0
	v_lshl_add_u64 v[38:39], v[38:39], 0, v[40:41]
	v_mul_f32_e32 v0, v0, v42
	v_mul_f32_e32 v1, v1, v42
	v_mul_f32_e32 v2, v2, v42
	v_mul_f32_e32 v3, v3, v42
	v_mul_f32_e32 v4, v4, v42
	v_mul_f32_e32 v5, v5, v42
	v_mul_f32_e32 v6, v6, v42
	v_mul_f32_e32 v7, v7, v42
	v_cvt_pk_bf16_f32 v0, v0, v1
	v_cvt_pk_bf16_f32 v1, v2, v3
	v_cvt_pk_bf16_f32 v2, v4, v5
	v_cvt_pk_bf16_f32 v3, v6, v7
	s_nop 1
	v_permlane32_swap_b32 v0, v2
	v_permlane32_swap_b32 v1, v3
	global_store_dwordx4 v[38:39], v[0:3], off
	v_mul_f32_e32 v8, v8, v42
	v_mul_f32_e32 v9, v9, v42
	v_mul_f32_e32 v10, v10, v42
	v_mul_f32_e32 v11, v11, v42
	v_mul_f32_e32 v12, v12, v42
	v_mul_f32_e32 v13, v13, v42
	v_mul_f32_e32 v14, v14, v42
	v_mul_f32_e32 v15, v15, v42
	v_cvt_pk_bf16_f32 v8, v8, v9
	v_cvt_pk_bf16_f32 v9, v10, v11
	v_cvt_pk_bf16_f32 v10, v12, v13
	v_cvt_pk_bf16_f32 v11, v14, v15
	s_nop 1
	v_permlane32_swap_b32 v8, v10
	v_permlane32_swap_b32 v9, v11
	global_store_dwordx4 v[38:39], v[8:11], off offset:32
	v_mul_f32_e32 v16, v16, v42
	v_mul_f32_e32 v17, v17, v42
	v_mul_f32_e32 v18, v18, v42
	v_mul_f32_e32 v19, v19, v42
	v_mul_f32_e32 v20, v20, v42
	v_mul_f32_e32 v21, v21, v42
	v_mul_f32_e32 v22, v22, v42
	v_mul_f32_e32 v23, v23, v42
	v_cvt_pk_bf16_f32 v16, v16, v17
	v_cvt_pk_bf16_f32 v17, v18, v19
	v_cvt_pk_bf16_f32 v18, v20, v21
	v_cvt_pk_bf16_f32 v19, v22, v23
	s_nop 1
	v_permlane32_swap_b32 v16, v18
	v_permlane32_swap_b32 v17, v19
	global_store_dwordx4 v[38:39], v[16:19], off offset:64
	v_mul_f32_e32 v24, v24, v42
	v_mul_f32_e32 v25, v25, v42
	v_mul_f32_e32 v26, v26, v42
	v_mul_f32_e32 v27, v27, v42
	v_mul_f32_e32 v28, v28, v42
	v_mul_f32_e32 v29, v29, v42
	v_mul_f32_e32 v30, v30, v42
	v_mul_f32_e32 v31, v31, v42
	v_cvt_pk_bf16_f32 v24, v24, v25
	v_cvt_pk_bf16_f32 v25, v26, v27
	v_cvt_pk_bf16_f32 v26, v28, v29
	v_cvt_pk_bf16_f32 v27, v30, v31
	s_nop 1
	v_permlane32_swap_b32 v24, v26
	v_permlane32_swap_b32 v25, v27
	global_store_dwordx4 v[38:39], v[24:27], off offset:96
	s_and_saveexec_b64 s[4:5], s[8:9]
	s_cbranch_execz .LBB0_2969
	v_log_f32_e32 v2, v36
	v_readlane_b32 s8, v255, 22
	v_readlane_b32 s9, v255, 23
	s_mov_b32 s1, s17
	v_add_f32_e32 v4, v37, v2
	v_mad_u64_u32 v[0:1], s[8:9], v34, 48, s[8:9]
	v_mov_b32_e32 v2, v1
	v_mad_u64_u32 v[2:3], s[8:9], v32, 48, v[2:3]
	v_mov_b32_e32 v1, v2
	v_lshl_add_u64 v[0:1], s[0:1], 2, v[0:1]
	global_store_dword v[0:1], v4, off
	s_branch .LBB0_2969
